# speedup vs baseline: 1.0247x; 1.0031x over previous
; #define WAITV8(n) asm volatile("s_waitcnt vmcnt(" #n ")" ::: "memory")
; #define BAR8 __builtin_amdgcn_s_barrier()
; template <class Epi>
; DEV void gemm8_phase(const u16* __restrict__ A, int lda, const u16* __restrict__ Bt, int K, int nM, int nN, char* shmc, const Epi& epi) {
;     ...
;   for (int t = blockIdx.x; t < nwg; t += gridDim.x) {
;     int brow, bcol;
;     tile_coords(t, nwg, nM, nN, brow, bcol);
;     WAITV8(0);
;     __syncthreads();
;     f32x4 acc[2][2][4][2];
; #pragma unroll
;     for (int a_ = 0; a_ < 2; ++a_)
; #pragma unroll
;       for (int b_ = 0; b_ < 2; ++b_)
; #pragma unroll
;         for (int m = 0; m < 4; ++m)
; #pragma unroll
;           for (int n = 0; n < 2; ++n) acc[a_][b_][m][n] = f32x4{0.f, 0.f, 0.f, 0.f};
;     bf16x8 At[4][2], B0[2][2], B1[2][2];
;     if (!pref) {
;       STAGE8(SB8(0, 0), Bt, K, bcol, 0); STAGE8(SA8(0, 0), A, lda, brow, 0);
;       STAGE8(SB8(0, 1), Bt, K, bcol + HALF, 0); STAGE8(SA8(0, 1), A, lda, brow + HALF, 0);
;     }
;     if (wr == 1) BAR8;
;     WAITV8(4); BAR8;
;     STAGE8(SB8(1, 0), Bt, K, bcol, 1); STAGE8(SA8(1, 0), A, lda, brow, 1); STAGE8(SB8(1, 1), Bt, K, bcol + HALF, 1);
;     WAITV8(6); BAR8;
.LBB0_337:
	s_ashr_i32 s13, s12, 31
	s_lshl_b64 s[0:1], s[12:13], 12
	s_add_u32 s14, s84, s0
	s_addc_u32 s15, s85, s1
	s_ashr_i32 s7, s6, 31
	s_lshl_b64 s[0:1], s[6:7], 12
	s_add_u32 s16, s94, s0
	s_addc_u32 s17, s95, s1
	s_or_b32 s0, s12, 0x80
	s_mov_b32 m0, s55
	s_waitcnt lgkmcnt(0)
	v_lshl_add_u64 v[0:1], s[14:15], 0, v[134:135]
	s_ashr_i32 s1, s0, 31
	s_waitcnt vmcnt(4)
	s_barrier
	global_load_lds_dwordx4 v[0:1], off
	v_lshl_add_u64 v[0:1], s[14:15], 0, v[136:137]
	s_mov_b32 m0, s62
	s_lshl_b64 s[0:1], s[0:1], 12
	global_load_lds_dwordx4 v[0:1], off
	v_lshl_add_u64 v[0:1], s[16:17], 0, v[134:135]
	s_mov_b32 m0, s63
	s_add_u32 s22, s84, s0
	global_load_lds_dwordx4 v[0:1], off
	v_lshl_add_u64 v[0:1], s[16:17], 0, v[136:137]
	s_mov_b32 m0, s70
	s_addc_u32 s23, s85, s1
	global_load_lds_dwordx4 v[0:1], off
	v_lshl_add_u64 v[0:1], s[22:23], 0, v[134:135]
	s_mov_b32 m0, s71
	s_or_b32 s0, s6, 0x80
	global_load_lds_dwordx4 v[0:1], off
	v_lshl_add_u64 v[0:1], s[22:23], 0, v[136:137]
	s_mov_b32 m0, s72
	s_ashr_i32 s1, s0, 31
	global_load_lds_dwordx4 v[0:1], off
	s_waitcnt vmcnt(6)
	s_lshl_b64 s[0:1], s[0:1], 12
	s_add_u32 s18, s94, s0
	v_mov_b32_e32 v0, 0
	s_addc_u32 s19, s95, s1
	s_mov_b32 s0, -2
	s_mov_b32 s1, 0
	v_mov_b32_e32 v1, v0
	v_mov_b32_e32 v2, v0
	v_mov_b32_e32 v3, v0
	v_mov_b32_e32 v4, v0
	v_mov_b32_e32 v5, v0
	v_mov_b32_e32 v6, v0
	v_mov_b32_e32 v7, v0
	v_mov_b32_e32 v8, v0
	v_mov_b32_e32 v9, v0
	v_mov_b32_e32 v10, v0
	v_mov_b32_e32 v11, v0
	v_mov_b32_e32 v12, v0
	v_mov_b32_e32 v13, v0
	v_mov_b32_e32 v14, v0
	v_mov_b32_e32 v15, v0
	v_mov_b32_e32 v16, v0
	v_mov_b32_e32 v17, v0
	v_mov_b32_e32 v18, v0
	v_mov_b32_e32 v19, v0
	v_mov_b32_e32 v20, v0
	v_mov_b32_e32 v21, v0
	v_mov_b32_e32 v22, v0
	v_mov_b32_e32 v23, v0
	v_mov_b32_e32 v24, v0
	v_mov_b32_e32 v25, v0
	v_mov_b32_e32 v26, v0
	v_mov_b32_e32 v27, v0
	v_mov_b32_e32 v28, v0
	v_mov_b32_e32 v29, v0
	v_mov_b32_e32 v30, v0
	v_mov_b32_e32 v31, v0
	v_mov_b32_e32 v32, v0
	v_mov_b32_e32 v33, v0
	v_mov_b32_e32 v34, v0
	v_mov_b32_e32 v35, v0
	v_mov_b32_e32 v36, v0
	v_mov_b32_e32 v37, v0
	v_mov_b32_e32 v38, v0
	v_mov_b32_e32 v39, v0
	v_mov_b32_e32 v40, v0
	v_mov_b32_e32 v41, v0
	v_mov_b32_e32 v42, v0
	v_mov_b32_e32 v43, v0
	v_mov_b32_e32 v44, v0
	v_mov_b32_e32 v45, v0
	v_mov_b32_e32 v46, v0
	v_mov_b32_e32 v47, v0
	v_mov_b32_e32 v48, v0
	v_mov_b32_e32 v49, v0
	v_mov_b32_e32 v50, v0
	v_mov_b32_e32 v51, v0
	v_mov_b32_e32 v52, v0
	v_mov_b32_e32 v53, v0
	v_mov_b32_e32 v54, v0
	v_mov_b32_e32 v55, v0
	v_mov_b32_e32 v56, v0
	v_mov_b32_e32 v57, v0
	v_mov_b32_e32 v58, v0
	v_mov_b32_e32 v59, v0
	v_mov_b32_e32 v60, v0
	v_mov_b32_e32 v61, v0
	v_mov_b32_e32 v62, v0
	v_mov_b32_e32 v63, v0
	v_mov_b32_e32 v64, v0
	v_mov_b32_e32 v65, v0
	v_mov_b32_e32 v66, v0
	v_mov_b32_e32 v67, v0
	v_mov_b32_e32 v68, v0
	v_mov_b32_e32 v69, v0
	v_mov_b32_e32 v70, v0
	v_mov_b32_e32 v71, v0
	v_mov_b32_e32 v72, v0
	v_mov_b32_e32 v73, v0
	v_mov_b32_e32 v74, v0
	v_mov_b32_e32 v75, v0
	v_mov_b32_e32 v76, v0
	v_mov_b32_e32 v77, v0
	v_mov_b32_e32 v78, v0
	v_mov_b32_e32 v79, v0
	v_mov_b32_e32 v80, v0
	v_mov_b32_e32 v81, v0
	v_mov_b32_e32 v82, v0
	v_mov_b32_e32 v83, v0
	v_mov_b32_e32 v84, v0
	v_mov_b32_e32 v85, v0
	v_mov_b32_e32 v86, v0
	v_mov_b32_e32 v87, v0
	v_mov_b32_e32 v88, v0
	v_mov_b32_e32 v89, v0
	v_mov_b32_e32 v90, v0
	v_mov_b32_e32 v91, v0
	v_mov_b32_e32 v92, v0
	v_mov_b32_e32 v93, v0
	v_mov_b32_e32 v94, v0
	v_mov_b32_e32 v95, v0
	v_mov_b32_e32 v96, v0
	v_mov_b32_e32 v97, v0
	v_mov_b32_e32 v98, v0
	v_mov_b32_e32 v99, v0
	v_mov_b32_e32 v100, v0
	v_mov_b32_e32 v101, v0
	v_mov_b32_e32 v102, v0
	v_mov_b32_e32 v103, v0
	v_mov_b32_e32 v104, v0
	v_mov_b32_e32 v105, v0
	v_mov_b32_e32 v106, v0
	v_mov_b32_e32 v107, v0
	v_mov_b32_e32 v108, v0
	v_mov_b32_e32 v109, v0
	v_mov_b32_e32 v110, v0
	v_mov_b32_e32 v111, v0
	v_mov_b32_e32 v112, v0
	v_mov_b32_e32 v113, v0
	v_mov_b32_e32 v114, v0
	v_mov_b32_e32 v115, v0
	v_mov_b32_e32 v116, v0
	v_mov_b32_e32 v117, v0
	v_mov_b32_e32 v118, v0
	v_mov_b32_e32 v119, v0
	v_mov_b32_e32 v120, v0
	v_mov_b32_e32 v121, v0
	v_mov_b32_e32 v122, v0
	v_mov_b32_e32 v123, v0
	v_mov_b32_e32 v124, v0
	v_mov_b32_e32 v125, v0
	v_mov_b32_e32 v126, v0
	v_mov_b32_e32 v127, v0
	s_barrier
	.p2align 6

; #define WAITV8(n) asm volatile("s_waitcnt vmcnt(" #n ")" ::: "memory")
; #define BAR8 __builtin_amdgcn_s_barrier()
; template <class Epi>
; DEV void gemm8_phase(const u16* __restrict__ A, int lda, const u16* __restrict__ Bt, int K, int nM, int nN, char* shmc, const Epi& epi) {
;     ...
;   for (int t = blockIdx.x; t < nwg; t += gridDim.x) {
;     int brow, bcol;
;     tile_coords(t, nwg, nM, nN, brow, bcol);
;     WAITV8(0);
;     __syncthreads();
;     f32x4 acc[2][2][4][2];
; #pragma unroll
;     for (int a_ = 0; a_ < 2; ++a_)
; #pragma unroll
;       for (int b_ = 0; b_ < 2; ++b_)
; #pragma unroll
;         for (int m = 0; m < 4; ++m)
; #pragma unroll
;           for (int n = 0; n < 2; ++n) acc[a_][b_][m][n] = f32x4{0.f, 0.f, 0.f, 0.f};
;     bf16x8 At[4][2], B0[2][2], B1[2][2];
;     if (!pref) {
;       STAGE8(SB8(0, 0), Bt, K, bcol, 0); STAGE8(SA8(0, 0), A, lda, brow, 0);
;       STAGE8(SB8(0, 1), Bt, K, bcol + HALF, 0); STAGE8(SA8(0, 1), A, lda, brow + HALF, 0);
;     }
;     if (wr == 1) BAR8;
;     WAITV8(4); BAR8;
;     STAGE8(SB8(1, 0), Bt, K, bcol, 1); STAGE8(SA8(1, 0), A, lda, brow, 1); STAGE8(SB8(1, 1), Bt, K, bcol + HALF, 1);
;     WAITV8(6); BAR8;
.LBB0_407:
	s_ashr_i32 s19, s18, 31
	s_lshl_b64 s[0:1], s[18:19], 12
	s_add_u32 s14, s64, s0
	s_addc_u32 s15, s65, s1
	s_ashr_i32 s17, s16, 31
	s_lshl_b64 s[0:1], s[16:17], 12
	s_add_u32 s22, s20, s0
	s_addc_u32 s23, s21, s1
	s_or_b32 s0, s18, 0x80
	s_mov_b32 m0, s39
	v_lshl_add_u64 v[0:1], s[14:15], 0, v[134:135]
	s_ashr_i32 s1, s0, 31
	s_waitcnt vmcnt(4)
	s_barrier
	global_load_lds_dwordx4 v[0:1], off
	v_lshl_add_u64 v[0:1], s[14:15], 0, v[136:137]
	s_mov_b32 m0, s54
	s_lshl_b64 s[0:1], s[0:1], 12
	global_load_lds_dwordx4 v[0:1], off
	v_lshl_add_u64 v[0:1], s[22:23], 0, v[134:135]
	s_mov_b32 m0, s55
	s_add_u32 s26, s64, s0
	global_load_lds_dwordx4 v[0:1], off
	v_lshl_add_u64 v[0:1], s[22:23], 0, v[136:137]
	s_mov_b32 m0, s62
	s_addc_u32 s27, s65, s1
	global_load_lds_dwordx4 v[0:1], off
	v_lshl_add_u64 v[0:1], s[26:27], 0, v[134:135]
	s_mov_b32 m0, s63
	s_or_b32 s0, s16, 0x80
	global_load_lds_dwordx4 v[0:1], off
	v_lshl_add_u64 v[0:1], s[26:27], 0, v[136:137]
	s_mov_b32 m0, s70
	s_ashr_i32 s1, s0, 31
	global_load_lds_dwordx4 v[0:1], off
	s_waitcnt vmcnt(6)
	s_lshl_b64 s[0:1], s[0:1], 12
	s_add_u32 s24, s20, s0
	v_mov_b32_e32 v0, 0
	s_addc_u32 s25, s21, s1
	s_mov_b32 s0, -2
	v_mov_b32_e32 v132, v163
	v_mov_b32_e32 v142, v162
	v_mov_b32_e32 v1, v0
	v_mov_b32_e32 v2, v0
	v_mov_b32_e32 v3, v0
	v_mov_b32_e32 v4, v0
	v_mov_b32_e32 v5, v0
	v_mov_b32_e32 v6, v0
	v_mov_b32_e32 v7, v0
	v_mov_b32_e32 v8, v0
	v_mov_b32_e32 v9, v0
	v_mov_b32_e32 v10, v0
	v_mov_b32_e32 v11, v0
	v_mov_b32_e32 v12, v0
	v_mov_b32_e32 v13, v0
	v_mov_b32_e32 v14, v0
	v_mov_b32_e32 v15, v0
	v_mov_b32_e32 v16, v0
	v_mov_b32_e32 v17, v0
	v_mov_b32_e32 v18, v0
	v_mov_b32_e32 v19, v0
	v_mov_b32_e32 v20, v0
	v_mov_b32_e32 v21, v0
	v_mov_b32_e32 v22, v0
	v_mov_b32_e32 v23, v0
	v_mov_b32_e32 v24, v0
	v_mov_b32_e32 v25, v0
	v_mov_b32_e32 v26, v0
	v_mov_b32_e32 v27, v0
	v_mov_b32_e32 v28, v0
	v_mov_b32_e32 v29, v0
	v_mov_b32_e32 v30, v0
	v_mov_b32_e32 v31, v0
	v_mov_b32_e32 v32, v0
	v_mov_b32_e32 v33, v0
	v_mov_b32_e32 v34, v0
	v_mov_b32_e32 v35, v0
	v_mov_b32_e32 v36, v0
	v_mov_b32_e32 v37, v0
	v_mov_b32_e32 v38, v0
	v_mov_b32_e32 v39, v0
	v_mov_b32_e32 v40, v0
	v_mov_b32_e32 v41, v0
	v_mov_b32_e32 v42, v0
	v_mov_b32_e32 v43, v0
	v_mov_b32_e32 v44, v0
	v_mov_b32_e32 v45, v0
	v_mov_b32_e32 v46, v0
	v_mov_b32_e32 v47, v0
	v_mov_b32_e32 v48, v0
	v_mov_b32_e32 v49, v0
	v_mov_b32_e32 v50, v0
	v_mov_b32_e32 v51, v0
	v_mov_b32_e32 v52, v0
	v_mov_b32_e32 v53, v0
	v_mov_b32_e32 v54, v0
	v_mov_b32_e32 v55, v0
	v_mov_b32_e32 v56, v0
	v_mov_b32_e32 v57, v0
	v_mov_b32_e32 v58, v0
	v_mov_b32_e32 v59, v0
	v_mov_b32_e32 v60, v0
	v_mov_b32_e32 v61, v0
	v_mov_b32_e32 v62, v0
	v_mov_b32_e32 v63, v0
	v_mov_b32_e32 v64, v0
	v_mov_b32_e32 v65, v0
	v_mov_b32_e32 v66, v0
	v_mov_b32_e32 v67, v0
	v_mov_b32_e32 v68, v0
	v_mov_b32_e32 v69, v0
	v_mov_b32_e32 v70, v0
	v_mov_b32_e32 v71, v0
	v_mov_b32_e32 v72, v0
	v_mov_b32_e32 v73, v0
	v_mov_b32_e32 v74, v0
	v_mov_b32_e32 v75, v0
	v_mov_b32_e32 v76, v0
	v_mov_b32_e32 v77, v0
	v_mov_b32_e32 v78, v0
	v_mov_b32_e32 v79, v0
	v_mov_b32_e32 v80, v0
	v_mov_b32_e32 v81, v0
	v_mov_b32_e32 v82, v0
	v_mov_b32_e32 v83, v0
	v_mov_b32_e32 v84, v0
	v_mov_b32_e32 v85, v0
	v_mov_b32_e32 v86, v0
	v_mov_b32_e32 v87, v0
	v_mov_b32_e32 v88, v0
	v_mov_b32_e32 v89, v0
	v_mov_b32_e32 v90, v0
	v_mov_b32_e32 v91, v0
	v_mov_b32_e32 v92, v0
	v_mov_b32_e32 v93, v0
	v_mov_b32_e32 v94, v0
	v_mov_b32_e32 v95, v0
	v_mov_b32_e32 v96, v0
	v_mov_b32_e32 v97, v0
	v_mov_b32_e32 v98, v0
	v_mov_b32_e32 v99, v0
	v_mov_b32_e32 v100, v0
	v_mov_b32_e32 v101, v0
	v_mov_b32_e32 v102, v0
	v_mov_b32_e32 v103, v0
	v_mov_b32_e32 v104, v0
	v_mov_b32_e32 v105, v0
	v_mov_b32_e32 v106, v0
	v_mov_b32_e32 v107, v0
	v_mov_b32_e32 v108, v0
	v_mov_b32_e32 v109, v0
	v_mov_b32_e32 v110, v0
	v_mov_b32_e32 v111, v0
	v_mov_b32_e32 v112, v0
	v_mov_b32_e32 v113, v0
	v_mov_b32_e32 v114, v0
	v_mov_b32_e32 v115, v0
	v_mov_b32_e32 v116, v0
	v_mov_b32_e32 v117, v0
	v_mov_b32_e32 v118, v0
	v_mov_b32_e32 v119, v0
	v_mov_b32_e32 v120, v0
	v_mov_b32_e32 v121, v0
	v_mov_b32_e32 v122, v0
	v_mov_b32_e32 v123, v0
	v_mov_b32_e32 v124, v0
	v_mov_b32_e32 v125, v0
	v_mov_b32_e32 v126, v0
	v_mov_b32_e32 v127, v0
	s_barrier
	.p2align 6

; #define WAITV8(n) asm volatile("s_waitcnt vmcnt(" #n ")" ::: "memory")
; #define BAR8 __builtin_amdgcn_s_barrier()
; template <class Epi>
; DEV void gemm8_phase(const u16* __restrict__ A, int lda, const u16* __restrict__ Bt, int K, int nM, int nN, char* shmc, const Epi& epi) {
;     ...
;   for (int t = blockIdx.x; t < nwg; t += gridDim.x) {
;     int brow, bcol;
;     tile_coords(t, nwg, nM, nN, brow, bcol);
;     WAITV8(0);
;     __syncthreads();
;     f32x4 acc[2][2][4][2];
; #pragma unroll
;     for (int a_ = 0; a_ < 2; ++a_)
; #pragma unroll
;       for (int b_ = 0; b_ < 2; ++b_)
; #pragma unroll
;         for (int m = 0; m < 4; ++m)
; #pragma unroll
;           for (int n = 0; n < 2; ++n) acc[a_][b_][m][n] = f32x4{0.f, 0.f, 0.f, 0.f};
;     bf16x8 At[4][2], B0[2][2], B1[2][2];
;     if (!pref) {
;       STAGE8(SB8(0, 0), Bt, K, bcol, 0); STAGE8(SA8(0, 0), A, lda, brow, 0);
;       STAGE8(SB8(0, 1), Bt, K, bcol + HALF, 0); STAGE8(SA8(0, 1), A, lda, brow + HALF, 0);
;     }
;     if (wr == 1) BAR8;
;     WAITV8(4); BAR8;
;     STAGE8(SB8(1, 0), Bt, K, bcol, 1); STAGE8(SA8(1, 0), A, lda, brow, 1); STAGE8(SB8(1, 1), Bt, K, bcol + HALF, 1);
;     WAITV8(6); BAR8;
.LBB0_430:
	s_ashr_i32 s7, s6, 31
	s_lshl_b64 s[6:7], s[6:7], 1
	s_add_u32 s6, s58, s6
	s_addc_u32 s7, s59, s7
	s_mov_b32 m0, s29
	s_waitcnt lgkmcnt(0)
	v_lshl_add_u64 v[0:1], s[6:7], 0, v[134:135]
	s_add_u32 s14, s10, s14
	s_waitcnt vmcnt(4)
	s_barrier
	global_load_lds_dwordx4 v[0:1], off
	v_lshl_add_u64 v[0:1], s[6:7], 0, v[136:137]
	s_mov_b32 m0, s30
	s_addc_u32 s15, s11, s15
	global_load_lds_dwordx4 v[0:1], off
	v_lshl_add_u64 v[0:1], s[14:15], 0, v[134:135]
	s_mov_b32 m0, s31
	s_add_u32 s18, s6, 0x160000
	global_load_lds_dwordx4 v[0:1], off
	v_lshl_add_u64 v[0:1], s[14:15], 0, v[136:137]
	s_mov_b32 m0, s34
	s_addc_u32 s19, s7, 0
	global_load_lds_dwordx4 v[0:1], off
	v_lshl_add_u64 v[0:1], s[18:19], 0, v[134:135]
	s_mov_b32 m0, s35
	s_or_b32 s16, s0, 0x80
	global_load_lds_dwordx4 v[0:1], off
	v_lshl_add_u64 v[0:1], s[18:19], 0, v[136:137]
	s_mov_b32 m0, s36
	s_mul_hi_i32 s17, s16, 0x2c00
	global_load_lds_dwordx4 v[0:1], off
	s_waitcnt vmcnt(6)
	s_mulk_i32 s16, 0x2c00
	s_add_u32 s16, s10, s16
	v_mov_b32_e32 v0, 0
	s_addc_u32 s17, s11, s17
	s_mov_b32 s54, -2
	v_mov_b32_e32 v132, v153
	v_mov_b32_e32 v142, v152
	v_mov_b32_e32 v1, v0
	v_mov_b32_e32 v2, v0
	v_mov_b32_e32 v3, v0
	v_mov_b32_e32 v4, v0
	v_mov_b32_e32 v5, v0
	v_mov_b32_e32 v6, v0
	v_mov_b32_e32 v7, v0
	v_mov_b32_e32 v8, v0
	v_mov_b32_e32 v9, v0
	v_mov_b32_e32 v10, v0
	v_mov_b32_e32 v11, v0
	v_mov_b32_e32 v12, v0
	v_mov_b32_e32 v13, v0
	v_mov_b32_e32 v14, v0
	v_mov_b32_e32 v15, v0
	v_mov_b32_e32 v16, v0
	v_mov_b32_e32 v17, v0
	v_mov_b32_e32 v18, v0
	v_mov_b32_e32 v19, v0
	v_mov_b32_e32 v20, v0
	v_mov_b32_e32 v21, v0
	v_mov_b32_e32 v22, v0
	v_mov_b32_e32 v23, v0
	v_mov_b32_e32 v24, v0
	v_mov_b32_e32 v25, v0
	v_mov_b32_e32 v26, v0
	v_mov_b32_e32 v27, v0
	v_mov_b32_e32 v28, v0
	v_mov_b32_e32 v29, v0
	v_mov_b32_e32 v30, v0
	v_mov_b32_e32 v31, v0
	v_mov_b32_e32 v32, v0
	v_mov_b32_e32 v33, v0
	v_mov_b32_e32 v34, v0
	v_mov_b32_e32 v35, v0
	v_mov_b32_e32 v36, v0
	v_mov_b32_e32 v37, v0
	v_mov_b32_e32 v38, v0
	v_mov_b32_e32 v39, v0
	v_mov_b32_e32 v40, v0
	v_mov_b32_e32 v41, v0
	v_mov_b32_e32 v42, v0
	v_mov_b32_e32 v43, v0
	v_mov_b32_e32 v44, v0
	v_mov_b32_e32 v45, v0
	v_mov_b32_e32 v46, v0
	v_mov_b32_e32 v47, v0
	v_mov_b32_e32 v48, v0
	v_mov_b32_e32 v49, v0
	v_mov_b32_e32 v50, v0
	v_mov_b32_e32 v51, v0
	v_mov_b32_e32 v52, v0
	v_mov_b32_e32 v53, v0
	v_mov_b32_e32 v54, v0
	v_mov_b32_e32 v55, v0
	v_mov_b32_e32 v56, v0
	v_mov_b32_e32 v57, v0
	v_mov_b32_e32 v58, v0
	v_mov_b32_e32 v59, v0
	v_mov_b32_e32 v60, v0
	v_mov_b32_e32 v61, v0
	v_mov_b32_e32 v62, v0
	v_mov_b32_e32 v63, v0
	v_mov_b32_e32 v64, v0
	v_mov_b32_e32 v65, v0
	v_mov_b32_e32 v66, v0
	v_mov_b32_e32 v67, v0
	v_mov_b32_e32 v68, v0
	v_mov_b32_e32 v69, v0
	v_mov_b32_e32 v70, v0
	v_mov_b32_e32 v71, v0
	v_mov_b32_e32 v72, v0
	v_mov_b32_e32 v73, v0
	v_mov_b32_e32 v74, v0
	v_mov_b32_e32 v75, v0
	v_mov_b32_e32 v76, v0
	v_mov_b32_e32 v77, v0
	v_mov_b32_e32 v78, v0
	v_mov_b32_e32 v79, v0
	v_mov_b32_e32 v80, v0
	v_mov_b32_e32 v81, v0
	v_mov_b32_e32 v82, v0
	v_mov_b32_e32 v83, v0
	v_mov_b32_e32 v84, v0
	v_mov_b32_e32 v85, v0
	v_mov_b32_e32 v86, v0
	v_mov_b32_e32 v87, v0
	v_mov_b32_e32 v88, v0
	v_mov_b32_e32 v89, v0
	v_mov_b32_e32 v90, v0
	v_mov_b32_e32 v91, v0
	v_mov_b32_e32 v92, v0
	v_mov_b32_e32 v93, v0
	v_mov_b32_e32 v94, v0
	v_mov_b32_e32 v95, v0
	v_mov_b32_e32 v96, v0
	v_mov_b32_e32 v97, v0
	v_mov_b32_e32 v98, v0
	v_mov_b32_e32 v99, v0
	v_mov_b32_e32 v100, v0
	v_mov_b32_e32 v101, v0
	v_mov_b32_e32 v102, v0
	v_mov_b32_e32 v103, v0
	v_mov_b32_e32 v104, v0
	v_mov_b32_e32 v105, v0
	v_mov_b32_e32 v106, v0
	v_mov_b32_e32 v107, v0
	v_mov_b32_e32 v108, v0
	v_mov_b32_e32 v109, v0
	v_mov_b32_e32 v110, v0
	v_mov_b32_e32 v111, v0
	v_mov_b32_e32 v112, v0
	v_mov_b32_e32 v113, v0
	v_mov_b32_e32 v114, v0
	v_mov_b32_e32 v115, v0
	v_mov_b32_e32 v116, v0
	v_mov_b32_e32 v117, v0
	v_mov_b32_e32 v118, v0
	v_mov_b32_e32 v119, v0
	v_mov_b32_e32 v120, v0
	v_mov_b32_e32 v121, v0
	v_mov_b32_e32 v122, v0
	v_mov_b32_e32 v123, v0
	v_mov_b32_e32 v124, v0
	v_mov_b32_e32 v125, v0
	v_mov_b32_e32 v126, v0
	v_mov_b32_e32 v127, v0
	s_barrier
	.p2align 6

; #define WAITV8(n) asm volatile("s_waitcnt vmcnt(" #n ")" ::: "memory")
; #define BAR8 __builtin_amdgcn_s_barrier()
; template <class Epi>
; DEV void gemm8_phase(const u16* __restrict__ A, int lda, const u16* __restrict__ Bt, int K, int nM, int nN, char* shmc, const Epi& epi) {
;     ...
;   for (int t = blockIdx.x; t < nwg; t += gridDim.x) {
;     int brow, bcol;
;     tile_coords(t, nwg, nM, nN, brow, bcol);
;     WAITV8(0);
;     __syncthreads();
;     f32x4 acc[2][2][4][2];
; #pragma unroll
;     for (int a_ = 0; a_ < 2; ++a_)
; #pragma unroll
;       for (int b_ = 0; b_ < 2; ++b_)
; #pragma unroll
;         for (int m = 0; m < 4; ++m)
; #pragma unroll
;           for (int n = 0; n < 2; ++n) acc[a_][b_][m][n] = f32x4{0.f, 0.f, 0.f, 0.f};
;     bf16x8 At[4][2], B0[2][2], B1[2][2];
;     if (!pref) {
;       STAGE8(SB8(0, 0), Bt, K, bcol, 0); STAGE8(SA8(0, 0), A, lda, brow, 0);
;       STAGE8(SB8(0, 1), Bt, K, bcol + HALF, 0); STAGE8(SA8(0, 1), A, lda, brow + HALF, 0);
;     }
;     if (wr == 1) BAR8;
;     WAITV8(4); BAR8;
;     STAGE8(SB8(1, 0), Bt, K, bcol, 1); STAGE8(SA8(1, 0), A, lda, brow, 1); STAGE8(SB8(1, 1), Bt, K, bcol + HALF, 1);
;     WAITV8(6); BAR8;
.LBB0_1554:
	s_ashr_i32 s13, s12, 31
	s_lshl_b64 s[0:1], s[12:13], 12
	s_add_u32 s14, s60, s0
	s_addc_u32 s15, s61, s1
	s_ashr_i32 s7, s6, 31
	s_lshl_b64 s[0:1], s[6:7], 12
	s_add_u32 s16, s68, s0
	s_addc_u32 s17, s69, s1
	s_or_b32 s0, s12, 0x80
	s_mov_b32 m0, s30
	v_lshl_add_u64 v[0:1], s[14:15], 0, v[134:135]
	s_ashr_i32 s1, s0, 31
	s_waitcnt vmcnt(4)
	s_barrier
	global_load_lds_dwordx4 v[0:1], off
	v_lshl_add_u64 v[0:1], s[14:15], 0, v[136:137]
	s_mov_b32 m0, s31
	s_lshl_b64 s[0:1], s[0:1], 12
	global_load_lds_dwordx4 v[0:1], off
	v_lshl_add_u64 v[0:1], s[16:17], 0, v[134:135]
	s_mov_b32 m0, s34
	s_add_u32 s20, s60, s0
	global_load_lds_dwordx4 v[0:1], off
	v_lshl_add_u64 v[0:1], s[16:17], 0, v[136:137]
	s_mov_b32 m0, s35
	s_addc_u32 s21, s61, s1
	global_load_lds_dwordx4 v[0:1], off
	v_lshl_add_u64 v[0:1], s[20:21], 0, v[134:135]
	s_mov_b32 m0, s36
	s_or_b32 s0, s6, 0x80
	global_load_lds_dwordx4 v[0:1], off
	v_lshl_add_u64 v[0:1], s[20:21], 0, v[136:137]
	s_mov_b32 m0, s37
	s_ashr_i32 s1, s0, 31
	global_load_lds_dwordx4 v[0:1], off
	s_waitcnt vmcnt(6)
	s_lshl_b64 s[0:1], s[0:1], 12
	s_add_u32 s18, s68, s0
	v_mov_b32_e32 v0, 0
	s_addc_u32 s19, s69, s1
	s_mov_b32 s0, -2
	s_mov_b32 s1, 0
	v_mov_b32_e32 v1, v0
	v_mov_b32_e32 v2, v0
	v_mov_b32_e32 v3, v0
	v_mov_b32_e32 v4, v0
	s_waitcnt lgkmcnt(0)
	v_mov_b32_e32 v5, v0
	v_mov_b32_e32 v6, v0
	v_mov_b32_e32 v7, v0
	v_mov_b32_e32 v8, v0
	v_mov_b32_e32 v9, v0
	v_mov_b32_e32 v10, v0
	v_mov_b32_e32 v11, v0
	v_mov_b32_e32 v12, v0
	v_mov_b32_e32 v13, v0
	v_mov_b32_e32 v14, v0
	v_mov_b32_e32 v15, v0
	v_mov_b32_e32 v16, v0
	v_mov_b32_e32 v17, v0
	v_mov_b32_e32 v18, v0
	v_mov_b32_e32 v19, v0
	v_mov_b32_e32 v20, v0
	v_mov_b32_e32 v21, v0
	v_mov_b32_e32 v22, v0
	v_mov_b32_e32 v23, v0
	v_mov_b32_e32 v24, v0
	v_mov_b32_e32 v25, v0
	v_mov_b32_e32 v26, v0
	v_mov_b32_e32 v27, v0
	v_mov_b32_e32 v28, v0
	v_mov_b32_e32 v29, v0
	v_mov_b32_e32 v30, v0
	v_mov_b32_e32 v31, v0
	v_mov_b32_e32 v32, v0
	v_mov_b32_e32 v33, v0
	v_mov_b32_e32 v34, v0
	v_mov_b32_e32 v35, v0
	v_mov_b32_e32 v36, v0
	v_mov_b32_e32 v37, v0
	v_mov_b32_e32 v38, v0
	v_mov_b32_e32 v39, v0
	v_mov_b32_e32 v40, v0
	v_mov_b32_e32 v41, v0
	v_mov_b32_e32 v42, v0
	v_mov_b32_e32 v43, v0
	v_mov_b32_e32 v44, v0
	v_mov_b32_e32 v45, v0
	v_mov_b32_e32 v46, v0
	v_mov_b32_e32 v47, v0
	v_mov_b32_e32 v48, v0
	v_mov_b32_e32 v49, v0
	v_mov_b32_e32 v50, v0
	v_mov_b32_e32 v51, v0
	v_mov_b32_e32 v52, v0
	v_mov_b32_e32 v53, v0
	v_mov_b32_e32 v54, v0
	v_mov_b32_e32 v55, v0
	v_mov_b32_e32 v56, v0
	v_mov_b32_e32 v57, v0
	v_mov_b32_e32 v58, v0
	v_mov_b32_e32 v59, v0
	v_mov_b32_e32 v60, v0
	v_mov_b32_e32 v61, v0
	v_mov_b32_e32 v62, v0
	v_mov_b32_e32 v63, v0
	v_mov_b32_e32 v64, v0
	v_mov_b32_e32 v65, v0
	v_mov_b32_e32 v66, v0
	v_mov_b32_e32 v67, v0
	v_mov_b32_e32 v68, v0
	v_mov_b32_e32 v69, v0
	v_mov_b32_e32 v70, v0
	v_mov_b32_e32 v71, v0
	v_mov_b32_e32 v72, v0
	v_mov_b32_e32 v73, v0
	v_mov_b32_e32 v74, v0
	v_mov_b32_e32 v75, v0
	v_mov_b32_e32 v76, v0
	v_mov_b32_e32 v77, v0
	v_mov_b32_e32 v78, v0
	v_mov_b32_e32 v79, v0
	v_mov_b32_e32 v80, v0
	v_mov_b32_e32 v81, v0
	v_mov_b32_e32 v82, v0
	v_mov_b32_e32 v83, v0
	v_mov_b32_e32 v84, v0
	v_mov_b32_e32 v85, v0
	v_mov_b32_e32 v86, v0
	v_mov_b32_e32 v87, v0
	v_mov_b32_e32 v88, v0
	v_mov_b32_e32 v89, v0
	v_mov_b32_e32 v90, v0
	v_mov_b32_e32 v91, v0
	v_mov_b32_e32 v92, v0
	v_mov_b32_e32 v93, v0
	v_mov_b32_e32 v94, v0
	v_mov_b32_e32 v95, v0
	v_mov_b32_e32 v96, v0
	v_mov_b32_e32 v97, v0
	v_mov_b32_e32 v98, v0
	v_mov_b32_e32 v99, v0
	v_mov_b32_e32 v100, v0
	v_mov_b32_e32 v101, v0
	v_mov_b32_e32 v102, v0
	v_mov_b32_e32 v103, v0
	v_mov_b32_e32 v104, v0
	v_mov_b32_e32 v105, v0
	v_mov_b32_e32 v106, v0
	v_mov_b32_e32 v107, v0
	v_mov_b32_e32 v108, v0
	v_mov_b32_e32 v109, v0
	v_mov_b32_e32 v110, v0
	v_mov_b32_e32 v111, v0
	v_mov_b32_e32 v112, v0
	v_mov_b32_e32 v113, v0
	v_mov_b32_e32 v114, v0
	v_mov_b32_e32 v115, v0
	v_mov_b32_e32 v116, v0
	v_mov_b32_e32 v117, v0
	v_mov_b32_e32 v118, v0
	v_mov_b32_e32 v119, v0
	v_mov_b32_e32 v120, v0
	v_mov_b32_e32 v121, v0
	v_mov_b32_e32 v122, v0
	v_mov_b32_e32 v123, v0
	v_mov_b32_e32 v124, v0
	v_mov_b32_e32 v125, v0
	v_mov_b32_e32 v126, v0
	v_mov_b32_e32 v127, v0
	s_barrier
	.p2align 6

; #define WAITV8(n) asm volatile("s_waitcnt vmcnt(" #n ")" ::: "memory")
; #define BAR8 __builtin_amdgcn_s_barrier()
; template <class Epi>
; DEV void gemm8_phase(const u16* __restrict__ A, int lda, const u16* __restrict__ Bt, int K, int nM, int nN, char* shmc, const Epi& epi) {
;     ...
;   for (int t = blockIdx.x; t < nwg; t += gridDim.x) {
;     int brow, bcol;
;     tile_coords(t, nwg, nM, nN, brow, bcol);
;     WAITV8(0);
;     __syncthreads();
;     f32x4 acc[2][2][4][2];
; #pragma unroll
;     for (int a_ = 0; a_ < 2; ++a_)
; #pragma unroll
;       for (int b_ = 0; b_ < 2; ++b_)
; #pragma unroll
;         for (int m = 0; m < 4; ++m)
; #pragma unroll
;           for (int n = 0; n < 2; ++n) acc[a_][b_][m][n] = f32x4{0.f, 0.f, 0.f, 0.f};
;     bf16x8 At[4][2], B0[2][2], B1[2][2];
;     if (!pref) {
;       STAGE8(SB8(0, 0), Bt, K, bcol, 0); STAGE8(SA8(0, 0), A, lda, brow, 0);
;       STAGE8(SB8(0, 1), Bt, K, bcol + HALF, 0); STAGE8(SA8(0, 1), A, lda, brow + HALF, 0);
;     }
;     if (wr == 1) BAR8;
;     WAITV8(4); BAR8;
;     STAGE8(SB8(1, 0), Bt, K, bcol, 1); STAGE8(SA8(1, 0), A, lda, brow, 1); STAGE8(SB8(1, 1), Bt, K, bcol + HALF, 1);
;     WAITV8(6); BAR8;
.LBB0_1624:
	s_ashr_i32 s15, s14, 31
	s_lshl_b64 s[0:1], s[14:15], 12
	s_add_u32 s16, s52, s0
	s_addc_u32 s17, s53, s1
	s_ashr_i32 s13, s12, 31
	s_lshl_b64 s[0:1], s[12:13], 12
	s_add_u32 s18, s68, s0
	s_addc_u32 s19, s69, s1
	s_or_b32 s0, s14, 0x80
	s_mov_b32 m0, s34
	v_lshl_add_u64 v[0:1], s[16:17], 0, v[134:135]
	s_ashr_i32 s1, s0, 31
	s_waitcnt vmcnt(4)
	s_barrier
	global_load_lds_dwordx4 v[0:1], off
	v_lshl_add_u64 v[0:1], s[16:17], 0, v[136:137]
	s_mov_b32 m0, s35
	s_lshl_b64 s[0:1], s[0:1], 12
	global_load_lds_dwordx4 v[0:1], off
	v_lshl_add_u64 v[0:1], s[18:19], 0, v[134:135]
	s_mov_b32 m0, s36
	s_add_u32 s22, s52, s0
	global_load_lds_dwordx4 v[0:1], off
	v_lshl_add_u64 v[0:1], s[18:19], 0, v[136:137]
	s_mov_b32 m0, s37
	s_addc_u32 s23, s53, s1
	global_load_lds_dwordx4 v[0:1], off
	v_lshl_add_u64 v[0:1], s[22:23], 0, v[134:135]
	s_mov_b32 m0, s42
	s_or_b32 s0, s12, 0x80
	global_load_lds_dwordx4 v[0:1], off
	v_lshl_add_u64 v[0:1], s[22:23], 0, v[136:137]
	s_mov_b32 m0, s43
	s_ashr_i32 s1, s0, 31
	global_load_lds_dwordx4 v[0:1], off
	s_waitcnt vmcnt(6)
	s_lshl_b64 s[0:1], s[0:1], 12
	s_add_u32 s20, s68, s0
	v_mov_b32_e32 v0, 0
	s_addc_u32 s21, s69, s1
	s_mov_b32 s0, -2
	v_mov_b32_e32 v132, v159
	v_mov_b32_e32 v142, v158
	v_mov_b32_e32 v1, v0
	v_mov_b32_e32 v2, v0
	v_mov_b32_e32 v3, v0
	v_mov_b32_e32 v4, v0
	v_mov_b32_e32 v5, v0
	v_mov_b32_e32 v6, v0
	v_mov_b32_e32 v7, v0
	v_mov_b32_e32 v8, v0
	v_mov_b32_e32 v9, v0
	v_mov_b32_e32 v10, v0
	v_mov_b32_e32 v11, v0
	v_mov_b32_e32 v12, v0
	v_mov_b32_e32 v13, v0
	v_mov_b32_e32 v14, v0
	v_mov_b32_e32 v15, v0
	v_mov_b32_e32 v16, v0
	v_mov_b32_e32 v17, v0
	v_mov_b32_e32 v18, v0
	v_mov_b32_e32 v19, v0
	v_mov_b32_e32 v20, v0
	v_mov_b32_e32 v21, v0
	v_mov_b32_e32 v22, v0
	v_mov_b32_e32 v23, v0
	v_mov_b32_e32 v24, v0
	v_mov_b32_e32 v25, v0
	v_mov_b32_e32 v26, v0
	v_mov_b32_e32 v27, v0
	v_mov_b32_e32 v28, v0
	v_mov_b32_e32 v29, v0
	v_mov_b32_e32 v30, v0
	v_mov_b32_e32 v31, v0
	v_mov_b32_e32 v32, v0
	v_mov_b32_e32 v33, v0
	v_mov_b32_e32 v34, v0
	v_mov_b32_e32 v35, v0
	v_mov_b32_e32 v36, v0
	v_mov_b32_e32 v37, v0
	v_mov_b32_e32 v38, v0
	v_mov_b32_e32 v39, v0
	v_mov_b32_e32 v40, v0
	v_mov_b32_e32 v41, v0
	v_mov_b32_e32 v42, v0
	v_mov_b32_e32 v43, v0
	v_mov_b32_e32 v44, v0
	v_mov_b32_e32 v45, v0
	v_mov_b32_e32 v46, v0
	v_mov_b32_e32 v47, v0
	v_mov_b32_e32 v48, v0
	v_mov_b32_e32 v49, v0
	v_mov_b32_e32 v50, v0
	v_mov_b32_e32 v51, v0
	v_mov_b32_e32 v52, v0
	v_mov_b32_e32 v53, v0
	v_mov_b32_e32 v54, v0
	v_mov_b32_e32 v55, v0
	v_mov_b32_e32 v56, v0
	v_mov_b32_e32 v57, v0
	v_mov_b32_e32 v58, v0
	v_mov_b32_e32 v59, v0
	v_mov_b32_e32 v60, v0
	v_mov_b32_e32 v61, v0
	v_mov_b32_e32 v62, v0
	v_mov_b32_e32 v63, v0
	v_mov_b32_e32 v64, v0
	v_mov_b32_e32 v65, v0
	v_mov_b32_e32 v66, v0
	v_mov_b32_e32 v67, v0
	v_mov_b32_e32 v68, v0
	v_mov_b32_e32 v69, v0
	v_mov_b32_e32 v70, v0
	v_mov_b32_e32 v71, v0
	v_mov_b32_e32 v72, v0
	v_mov_b32_e32 v73, v0
	v_mov_b32_e32 v74, v0
	v_mov_b32_e32 v75, v0
	v_mov_b32_e32 v76, v0
	v_mov_b32_e32 v77, v0
	v_mov_b32_e32 v78, v0
	v_mov_b32_e32 v79, v0
	v_mov_b32_e32 v80, v0
	v_mov_b32_e32 v81, v0
	v_mov_b32_e32 v82, v0
	v_mov_b32_e32 v83, v0
	v_mov_b32_e32 v84, v0
	v_mov_b32_e32 v85, v0
	v_mov_b32_e32 v86, v0
	v_mov_b32_e32 v87, v0
	v_mov_b32_e32 v88, v0
	v_mov_b32_e32 v89, v0
	v_mov_b32_e32 v90, v0
	v_mov_b32_e32 v91, v0
	v_mov_b32_e32 v92, v0
	v_mov_b32_e32 v93, v0
	v_mov_b32_e32 v94, v0
	v_mov_b32_e32 v95, v0
	v_mov_b32_e32 v96, v0
	v_mov_b32_e32 v97, v0
	v_mov_b32_e32 v98, v0
	v_mov_b32_e32 v99, v0
	v_mov_b32_e32 v100, v0
	v_mov_b32_e32 v101, v0
	v_mov_b32_e32 v102, v0
	v_mov_b32_e32 v103, v0
	v_mov_b32_e32 v104, v0
	v_mov_b32_e32 v105, v0
	v_mov_b32_e32 v106, v0
	v_mov_b32_e32 v107, v0
	v_mov_b32_e32 v108, v0
	v_mov_b32_e32 v109, v0
	v_mov_b32_e32 v110, v0
	v_mov_b32_e32 v111, v0
	v_mov_b32_e32 v112, v0
	v_mov_b32_e32 v113, v0
	v_mov_b32_e32 v114, v0
	v_mov_b32_e32 v115, v0
	v_mov_b32_e32 v116, v0
	v_mov_b32_e32 v117, v0
	v_mov_b32_e32 v118, v0
	v_mov_b32_e32 v119, v0
	v_mov_b32_e32 v120, v0
	v_mov_b32_e32 v121, v0
	v_mov_b32_e32 v122, v0
	v_mov_b32_e32 v123, v0
	v_mov_b32_e32 v124, v0
	v_mov_b32_e32 v125, v0
	v_mov_b32_e32 v126, v0
	v_mov_b32_e32 v127, v0
	s_barrier
	.p2align 6

; #define WAITV8(n) asm volatile("s_waitcnt vmcnt(" #n ")" ::: "memory")
; #define BAR8 __builtin_amdgcn_s_barrier()
; template <class Epi>
; DEV void gemm8_phase(const u16* __restrict__ A, int lda, const u16* __restrict__ Bt, int K, int nM, int nN, char* shmc, const Epi& epi) {
;     ...
;   for (int t = blockIdx.x; t < nwg; t += gridDim.x) {
;     int brow, bcol;
;     tile_coords(t, nwg, nM, nN, brow, bcol);
;     WAITV8(0);
;     __syncthreads();
;     f32x4 acc[2][2][4][2];
; #pragma unroll
;     for (int a_ = 0; a_ < 2; ++a_)
; #pragma unroll
;       for (int b_ = 0; b_ < 2; ++b_)
; #pragma unroll
;         for (int m = 0; m < 4; ++m)
; #pragma unroll
;           for (int n = 0; n < 2; ++n) acc[a_][b_][m][n] = f32x4{0.f, 0.f, 0.f, 0.f};
;     bf16x8 At[4][2], B0[2][2], B1[2][2];
;     if (!pref) {
;       STAGE8(SB8(0, 0), Bt, K, bcol, 0); STAGE8(SA8(0, 0), A, lda, brow, 0);
;       STAGE8(SB8(0, 1), Bt, K, bcol + HALF, 0); STAGE8(SA8(0, 1), A, lda, brow + HALF, 0);
;     }
;     if (wr == 1) BAR8;
;     WAITV8(4); BAR8;
;     STAGE8(SB8(1, 0), Bt, K, bcol, 1); STAGE8(SA8(1, 0), A, lda, brow, 1); STAGE8(SB8(1, 1), Bt, K, bcol + HALF, 1);
;     WAITV8(6); BAR8;
.LBB0_1647:
	s_ashr_i32 s7, s6, 31
	s_lshl_b64 s[6:7], s[6:7], 1
	s_add_u32 s6, s40, s6
	s_addc_u32 s7, s41, s7
	s_mov_b32 m0, s26
	v_lshl_add_u64 v[0:1], s[6:7], 0, v[134:135]
	s_add_u32 s12, s38, s12
	s_waitcnt vmcnt(4)
	s_barrier
	global_load_lds_dwordx4 v[0:1], off
	v_lshl_add_u64 v[0:1], s[6:7], 0, v[136:137]
	s_mov_b32 m0, s27
	s_addc_u32 s13, s39, s13
	global_load_lds_dwordx4 v[0:1], off
	v_lshl_add_u64 v[0:1], s[12:13], 0, v[134:135]
	s_mov_b32 m0, s28
	s_add_u32 s16, s6, 0x160000
	global_load_lds_dwordx4 v[0:1], off
	v_lshl_add_u64 v[0:1], s[12:13], 0, v[136:137]
	s_mov_b32 m0, s29
	s_addc_u32 s17, s7, 0
	global_load_lds_dwordx4 v[0:1], off
	v_lshl_add_u64 v[0:1], s[16:17], 0, v[134:135]
	s_mov_b32 m0, s30
	s_or_b32 s14, s0, 0x80
	global_load_lds_dwordx4 v[0:1], off
	v_lshl_add_u64 v[0:1], s[16:17], 0, v[136:137]
	s_mov_b32 m0, s31
	s_mul_hi_i32 s15, s14, 0x2c00
	global_load_lds_dwordx4 v[0:1], off
	s_waitcnt vmcnt(6)
	s_mulk_i32 s14, 0x2c00
	s_add_u32 s14, s38, s14
	v_mov_b32_e32 v0, 0
	s_addc_u32 s15, s39, s15
	s_mov_b32 s36, -2
	v_mov_b32_e32 v132, v153
	v_mov_b32_e32 v142, v152
	v_mov_b32_e32 v1, v0
	v_mov_b32_e32 v2, v0
	v_mov_b32_e32 v3, v0
	v_mov_b32_e32 v4, v0
	s_waitcnt lgkmcnt(0)
	v_mov_b32_e32 v5, v0
	v_mov_b32_e32 v6, v0
	v_mov_b32_e32 v7, v0
	v_mov_b32_e32 v8, v0
	v_mov_b32_e32 v9, v0
	v_mov_b32_e32 v10, v0
	v_mov_b32_e32 v11, v0
	v_mov_b32_e32 v12, v0
	v_mov_b32_e32 v13, v0
	v_mov_b32_e32 v14, v0
	v_mov_b32_e32 v15, v0
	v_mov_b32_e32 v16, v0
	v_mov_b32_e32 v17, v0
	v_mov_b32_e32 v18, v0
	v_mov_b32_e32 v19, v0
	v_mov_b32_e32 v20, v0
	v_mov_b32_e32 v21, v0
	v_mov_b32_e32 v22, v0
	v_mov_b32_e32 v23, v0
	v_mov_b32_e32 v24, v0
	v_mov_b32_e32 v25, v0
	v_mov_b32_e32 v26, v0
	v_mov_b32_e32 v27, v0
	v_mov_b32_e32 v28, v0
	v_mov_b32_e32 v29, v0
	v_mov_b32_e32 v30, v0
	v_mov_b32_e32 v31, v0
	v_mov_b32_e32 v32, v0
	v_mov_b32_e32 v33, v0
	v_mov_b32_e32 v34, v0
	v_mov_b32_e32 v35, v0
	v_mov_b32_e32 v36, v0
	v_mov_b32_e32 v37, v0
	v_mov_b32_e32 v38, v0
	v_mov_b32_e32 v39, v0
	v_mov_b32_e32 v40, v0
	v_mov_b32_e32 v41, v0
	v_mov_b32_e32 v42, v0
	v_mov_b32_e32 v43, v0
	v_mov_b32_e32 v44, v0
	v_mov_b32_e32 v45, v0
	v_mov_b32_e32 v46, v0
	v_mov_b32_e32 v47, v0
	v_mov_b32_e32 v48, v0
	v_mov_b32_e32 v49, v0
	v_mov_b32_e32 v50, v0
	v_mov_b32_e32 v51, v0
	v_mov_b32_e32 v52, v0
	v_mov_b32_e32 v53, v0
	v_mov_b32_e32 v54, v0
	v_mov_b32_e32 v55, v0
	v_mov_b32_e32 v56, v0
	v_mov_b32_e32 v57, v0
	v_mov_b32_e32 v58, v0
	v_mov_b32_e32 v59, v0
	v_mov_b32_e32 v60, v0
	v_mov_b32_e32 v61, v0
	v_mov_b32_e32 v62, v0
	v_mov_b32_e32 v63, v0
	v_mov_b32_e32 v64, v0
	v_mov_b32_e32 v65, v0
	v_mov_b32_e32 v66, v0
	v_mov_b32_e32 v67, v0
	v_mov_b32_e32 v68, v0
	v_mov_b32_e32 v69, v0
	v_mov_b32_e32 v70, v0
	v_mov_b32_e32 v71, v0
	v_mov_b32_e32 v72, v0
	v_mov_b32_e32 v73, v0
	v_mov_b32_e32 v74, v0
	v_mov_b32_e32 v75, v0
	v_mov_b32_e32 v76, v0
	v_mov_b32_e32 v77, v0
	v_mov_b32_e32 v78, v0
	v_mov_b32_e32 v79, v0
	v_mov_b32_e32 v80, v0
	v_mov_b32_e32 v81, v0
	v_mov_b32_e32 v82, v0
	v_mov_b32_e32 v83, v0
	v_mov_b32_e32 v84, v0
	v_mov_b32_e32 v85, v0
	v_mov_b32_e32 v86, v0
	v_mov_b32_e32 v87, v0
	v_mov_b32_e32 v88, v0
	v_mov_b32_e32 v89, v0
	v_mov_b32_e32 v90, v0
	v_mov_b32_e32 v91, v0
	v_mov_b32_e32 v92, v0
	v_mov_b32_e32 v93, v0
	v_mov_b32_e32 v94, v0
	v_mov_b32_e32 v95, v0
	v_mov_b32_e32 v96, v0
	v_mov_b32_e32 v97, v0
	v_mov_b32_e32 v98, v0
	v_mov_b32_e32 v99, v0
	v_mov_b32_e32 v100, v0
	v_mov_b32_e32 v101, v0
	v_mov_b32_e32 v102, v0
	v_mov_b32_e32 v103, v0
	v_mov_b32_e32 v104, v0
	v_mov_b32_e32 v105, v0
	v_mov_b32_e32 v106, v0
	v_mov_b32_e32 v107, v0
	v_mov_b32_e32 v108, v0
	v_mov_b32_e32 v109, v0
	v_mov_b32_e32 v110, v0
	v_mov_b32_e32 v111, v0
	v_mov_b32_e32 v112, v0
	v_mov_b32_e32 v113, v0
	v_mov_b32_e32 v114, v0
	v_mov_b32_e32 v115, v0
	v_mov_b32_e32 v116, v0
	v_mov_b32_e32 v117, v0
	v_mov_b32_e32 v118, v0
	v_mov_b32_e32 v119, v0
	v_mov_b32_e32 v120, v0
	v_mov_b32_e32 v121, v0
	v_mov_b32_e32 v122, v0
	v_mov_b32_e32 v123, v0
	v_mov_b32_e32 v124, v0
	v_mov_b32_e32 v125, v0
	v_mov_b32_e32 v126, v0
	v_mov_b32_e32 v127, v0
	s_barrier
	.p2align 6
